# post-phase GEMM fused-norm epilogue: rs rows loaded once, shift/scale vectors once per 4 row-blocks (16 serialized round trips -> 4)
# baseline (speedup 1.0000x reference)
;     __device__ __forceinline__ void operator()(const f32x4 (&acc)[2][2][4][2], const Unit& u, int wr, int wc, int fr, int fq) const {
;     ...
;             const int c0 = u.pn * 256 + bj * 128 + wc * 32 + 8 * fq;
;             if (c0 >= INC) continue;
; #pragma unroll
;             for (int ai = 0; ai < 2; ++ai)
; #pragma unroll
;                 for (int m = 0; m < 4; ++m) {
;                     const int r = EPI_ROW(u, ai, wr, m, fr);
;                     f32x4 v0 = acc[ai][bj][m][0], v1 = acc[ai][bj][m][1];
;                     if (rs) {
;                         const float rstd = rsqrtf(rs[r] * (1.f / 1024.f) + EPS);
;                         const float* sp = shw + (size_t)batch_of(r) * INPAD + c0;
;                         v0 = v0 * rstd + *(const f32x4*)sp; v1 = v1 * rstd + *(const f32x4*)(sp + 4);
.LBB0_630:
	v_or_b32_e32 v130, s15, v143
	v_readlane_b32 s2, v252, 27
	v_cndmask_b32_e64 v132, 0, 1, s[72:73]
	v_or_b32_e32 v141, 16, v142
	v_or_b32_e32 v130, s2, v130
	s_movk_i32 s2, 0x720
	v_or_b32_e32 v140, 32, v142
	v_or_b32_e32 v131, 48, v142
	s_xor_b64 s[6:7], vcc, -1
	s_add_i32 s8, s4, 0x80
	v_cmp_gt_u32_e32 vcc, s2, v130
	v_cmp_ne_u32_e64 s[38:39], 1, v132
	s_and_saveexec_b64 s[20:21], vcc
	s_cbranch_execz .LBB0_766
	v_readlane_b32 s2, v252, 24
	s_add_i32 s15, s4, s2
	v_or_b32_e32 v134, s15, v142
	v_ashrrev_i32_e32 v135, 31, v134
	s_and_b64 vcc, exec, s[38:39]
	v_cmp_gt_i32_e64 s[40:41], s89, v134
	s_cbranch_vccnz .LBB0_633
	v_readlane_b32 s2, v251, 45
	v_readlane_b32 s3, v251, 46
	v_lshlrev_b32_e32 v136, 2, v130
	v_mov_b32_e32 v137, v5
	v_lshl_add_u64 v[132:133], v[134:135], 2, s[2:3]
	global_load_dword v143, v[132:133], off
	global_load_dword v232, v[132:133], off
	global_load_dword v233, v[132:133], off offset:64
	global_load_dword v234, v[132:133], off offset:128
	global_load_dword v235, v[132:133], off offset:192
	global_load_dword v236, v[132:133], off offset:512
	global_load_dword v237, v[132:133], off offset:576
	global_load_dword v238, v[132:133], off offset:640
	global_load_dword v239, v[132:133], off offset:704
	s_add_i32 s3, s15, 0xffff0000
	s_lshr_b32 s3, s3, 6
	s_ashr_i32 s2, s15, 12
	s_add_i32 s3, s3, 16
	v_mov_b32_e32 v132, s3
	v_mov_b32_e32 v133, s2
	v_cndmask_b32_e64 v132, v132, v133, s[40:41]
	v_ashrrev_i32_e32 v133, 31, v132
	v_lshlrev_b64 v[132:133], 13, v[132:133]
	v_lshl_add_u64 v[132:133], s[56:57], 0, v[132:133]
	v_lshl_add_u64 v[132:133], v[132:133], 0, v[136:137]
	global_load_dwordx4 v[136:139], v[132:133], off
	global_load_dwordx4 v[144:147], v[132:133], off offset:16
	s_waitcnt vmcnt(0)
	v_mov_b32_e32 v240, v136
	v_mov_b32_e32 v241, v137
	v_mov_b32_e32 v242, v138
	v_mov_b32_e32 v243, v139
	v_mov_b32_e32 v244, v144
	v_mov_b32_e32 v245, v145
	v_mov_b32_e32 v246, v146
	v_mov_b32_e32 v247, v147
	v_fmamk_f32 v132, v143, 0x3a800000, v214
	v_mul_f32_e32 v133, 0x4b800000, v132
	v_cmp_gt_f32_e32 vcc, s9, v132
	s_nop 1
	v_cndmask_b32_e32 v132, v132, v133, vcc
	v_rsq_f32_e32 v132, v132
	s_nop 0
	v_mul_f32_e32 v133, 0x45800000, v132
	v_cndmask_b32_e32 v132, v132, v133, vcc
	v_pk_fma_f32 v[128:129], v[128:129], v[132:133], v[138:139] op_sel_hi:[1,0,1]
	v_pk_fma_f32 v[126:127], v[126:127], v[132:133], v[136:137] op_sel_hi:[1,0,1]
	v_pk_fma_f32 v[124:125], v[124:125], v[132:133], v[146:147] op_sel_hi:[1,0,1]
	v_pk_fma_f32 v[122:123], v[122:123], v[132:133], v[144:145] op_sel_hi:[1,0,1]

;     __device__ __forceinline__ void operator()(const f32x4 (&acc)[2][2][4][2], const Unit& u, int wr, int wc, int fr, int fq) const {
;     ...
;                     const int r = EPI_ROW(u, ai, wr, m, fr);
;                     f32x4 v0 = acc[ai][bj][m][0], v1 = acc[ai][bj][m][1];
;                     if (rs) {
;                         const float rstd = rsqrtf(rs[r] * (1.f / 1024.f) + EPS);
;                         const float* sp = shw + (size_t)batch_of(r) * INPAD + c0;
;                         v0 = v0 * rstd + *(const f32x4*)sp; v1 = v1 * rstd + *(const f32x4*)(sp + 4);
.LBB0_676:
	s_nop 1
	v_or_b32_e32 v122, s15, v141
	v_ashrrev_i32_e32 v123, 31, v122
	s_and_b64 vcc, exec, s[38:39]
	v_cmp_gt_i32_e64 s[40:41], s89, v122
	s_cbranch_vccnz .LBB0_678
	v_readlane_b32 s2, v251, 45
	v_readlane_b32 s3, v251, 46
	v_lshlrev_b32_e32 v126, 2, v130
	v_mov_b32_e32 v127, v5
	v_lshl_add_u64 v[124:125], v[122:123], 2, s[2:3]
	s_nop 0
	s_add_i32 s3, s15, 0xffff0000
	s_lshr_b32 s3, s3, 6
	s_ashr_i32 s2, s15, 12
	s_add_i32 s3, s3, 16
	v_mov_b32_e32 v124, s3
	v_mov_b32_e32 v125, s2
	v_cndmask_b32_e64 v124, v124, v125, s[40:41]
	v_ashrrev_i32_e32 v125, 31, v124
	v_lshlrev_b64 v[124:125], 13, v[124:125]
	v_lshl_add_u64 v[124:125], s[56:57], 0, v[124:125]
	v_lshl_add_u64 v[128:129], v[124:125], 0, v[126:127]
	s_nop 0
	s_nop 0
	v_mov_b32_e32 v133, v233
	v_mov_b32_e32 v124, v240
	v_mov_b32_e32 v125, v241
	v_mov_b32_e32 v126, v242
	v_mov_b32_e32 v127, v243
	v_mov_b32_e32 v134, v244
	v_mov_b32_e32 v135, v245
	v_mov_b32_e32 v136, v246
	v_mov_b32_e32 v137, v247
	v_fmamk_f32 v128, v133, 0x3a800000, v214
	v_mul_f32_e32 v129, 0x4b800000, v128
	v_cmp_gt_f32_e32 vcc, s9, v128
	s_nop 1
	v_cndmask_b32_e32 v128, v128, v129, vcc
	v_rsq_f32_e32 v128, v128
	s_nop 0
	v_mul_f32_e32 v129, 0x45800000, v128
	v_cndmask_b32_e32 v128, v128, v129, vcc
	v_pk_fma_f32 v[120:121], v[120:121], v[128:129], v[126:127] op_sel_hi:[1,0,1]
	v_pk_fma_f32 v[118:119], v[118:119], v[128:129], v[124:125] op_sel_hi:[1,0,1]
	v_pk_fma_f32 v[116:117], v[116:117], v[128:129], v[136:137] op_sel_hi:[1,0,1]
	v_pk_fma_f32 v[114:115], v[114:115], v[128:129], v[134:135] op_sel_hi:[1,0,1]

;     __device__ __forceinline__ void operator()(const f32x4 (&acc)[2][2][4][2], const Unit& u, int wr, int wc, int fr, int fq) const {
;     ...
;                     const int r = EPI_ROW(u, ai, wr, m, fr);
;                     f32x4 v0 = acc[ai][bj][m][0], v1 = acc[ai][bj][m][1];
;                     if (rs) {
;                         const float rstd = rsqrtf(rs[r] * (1.f / 1024.f) + EPS);
;                         const float* sp = shw + (size_t)batch_of(r) * INPAD + c0;
;                         v0 = v0 * rstd + *(const f32x4*)sp; v1 = v1 * rstd + *(const f32x4*)(sp + 4);
.LBB0_686:
	s_nop 1
	v_or_b32_e32 v114, s15, v140
	v_ashrrev_i32_e32 v115, 31, v114
	s_and_b64 vcc, exec, s[38:39]
	v_cmp_gt_i32_e64 s[42:43], s89, v114
	s_cbranch_vccnz .LBB0_688
	v_readlane_b32 s2, v251, 45
	v_readlane_b32 s3, v251, 46
	v_lshlrev_b32_e32 v118, 2, v130
	v_mov_b32_e32 v119, v5
	v_lshl_add_u64 v[116:117], v[114:115], 2, s[2:3]
	s_nop 0
	s_add_i32 s3, s15, 0xffff0000
	s_lshr_b32 s3, s3, 6
	s_ashr_i32 s2, s15, 12
	s_add_i32 s3, s3, 16
	v_mov_b32_e32 v116, s3
	v_mov_b32_e32 v117, s2
	v_cndmask_b32_e64 v116, v116, v117, s[42:43]
	v_ashrrev_i32_e32 v117, 31, v116
	v_lshlrev_b64 v[116:117], 13, v[116:117]
	v_lshl_add_u64 v[116:117], s[56:57], 0, v[116:117]
	v_lshl_add_u64 v[120:121], v[116:117], 0, v[118:119]
	s_nop 0
	s_nop 0
	s_nop 0
	v_mov_b32_e32 v124, v234
	v_mov_b32_e32 v116, v240
	v_mov_b32_e32 v117, v241
	v_mov_b32_e32 v118, v242
	v_mov_b32_e32 v119, v243
	v_mov_b32_e32 v120, v244
	v_mov_b32_e32 v121, v245
	v_mov_b32_e32 v122, v246
	v_mov_b32_e32 v123, v247
	v_fmamk_f32 v124, v124, 0x3a800000, v214
	v_mul_f32_e32 v125, 0x4b800000, v124
	v_cmp_gt_f32_e32 vcc, s9, v124
	s_nop 1
	v_cndmask_b32_e32 v124, v124, v125, vcc
	v_rsq_f32_e32 v124, v124
	s_nop 0
	v_mul_f32_e32 v125, 0x45800000, v124
	v_cndmask_b32_e32 v124, v124, v125, vcc
	v_pk_fma_f32 v[112:113], v[112:113], v[124:125], v[118:119] op_sel_hi:[1,0,1]
	v_pk_fma_f32 v[110:111], v[110:111], v[124:125], v[116:117] op_sel_hi:[1,0,1]
	v_pk_fma_f32 v[108:109], v[108:109], v[124:125], v[122:123] op_sel_hi:[1,0,1]
	v_pk_fma_f32 v[106:107], v[106:107], v[124:125], v[120:121] op_sel_hi:[1,0,1]

;     __device__ __forceinline__ void operator()(const f32x4 (&acc)[2][2][4][2], const Unit& u, int wr, int wc, int fr, int fq) const {
;     ...
;                     const int r = EPI_ROW(u, ai, wr, m, fr);
;                     f32x4 v0 = acc[ai][bj][m][0], v1 = acc[ai][bj][m][1];
;                     if (rs) {
;                         const float rstd = rsqrtf(rs[r] * (1.f / 1024.f) + EPS);
;                         const float* sp = shw + (size_t)batch_of(r) * INPAD + c0;
;                         v0 = v0 * rstd + *(const f32x4*)sp; v1 = v1 * rstd + *(const f32x4*)(sp + 4);
.LBB0_696:
	s_nop 1
	v_or_b32_e32 v106, s15, v131
	v_ashrrev_i32_e32 v107, 31, v106
	s_and_b64 vcc, exec, s[38:39]
	v_cmp_gt_i32_e64 s[42:43], s89, v106
	s_cbranch_vccnz .LBB0_698
	v_readlane_b32 s2, v251, 45
	v_readlane_b32 s3, v251, 46
	v_lshlrev_b32_e32 v110, 2, v130
	v_mov_b32_e32 v111, v5
	v_lshl_add_u64 v[108:109], v[106:107], 2, s[2:3]
	s_nop 0
	s_add_i32 s3, s15, 0xffff0000
	s_lshr_b32 s3, s3, 6
	s_ashr_i32 s2, s15, 12
	s_add_i32 s3, s3, 16
	v_mov_b32_e32 v108, s3
	v_mov_b32_e32 v109, s2
	v_cndmask_b32_e64 v108, v108, v109, s[42:43]
	v_ashrrev_i32_e32 v109, 31, v108
	v_lshlrev_b64 v[108:109], 13, v[108:109]
	v_lshl_add_u64 v[108:109], s[56:57], 0, v[108:109]
	v_lshl_add_u64 v[112:113], v[108:109], 0, v[110:111]
	s_nop 0
	s_nop 0
	s_nop 0
	v_mov_b32_e32 v116, v235
	v_mov_b32_e32 v108, v240
	v_mov_b32_e32 v109, v241
	v_mov_b32_e32 v110, v242
	v_mov_b32_e32 v111, v243
	v_mov_b32_e32 v112, v244
	v_mov_b32_e32 v113, v245
	v_mov_b32_e32 v114, v246
	v_mov_b32_e32 v115, v247
	v_fmamk_f32 v116, v116, 0x3a800000, v214
	v_mul_f32_e32 v117, 0x4b800000, v116
	v_cmp_gt_f32_e32 vcc, s9, v116
	s_nop 1
	v_cndmask_b32_e32 v116, v116, v117, vcc
	v_rsq_f32_e32 v116, v116
	s_nop 0
	v_mul_f32_e32 v117, 0x45800000, v116
	v_cndmask_b32_e32 v116, v116, v117, vcc
	v_pk_fma_f32 v[104:105], v[104:105], v[116:117], v[110:111] op_sel_hi:[1,0,1]
	v_pk_fma_f32 v[102:103], v[102:103], v[116:117], v[108:109] op_sel_hi:[1,0,1]
	v_pk_fma_f32 v[100:101], v[100:101], v[116:117], v[114:115] op_sel_hi:[1,0,1]
	v_pk_fma_f32 v[98:99], v[98:99], v[116:117], v[112:113] op_sel_hi:[1,0,1]

;     __device__ __forceinline__ void operator()(const f32x4 (&acc)[2][2][4][2], const Unit& u, int wr, int wc, int fr, int fq) const {
;     ...
;                     const int r = EPI_ROW(u, ai, wr, m, fr);
;                     f32x4 v0 = acc[ai][bj][m][0], v1 = acc[ai][bj][m][1];
;                     if (rs) {
;                         const float rstd = rsqrtf(rs[r] * (1.f / 1024.f) + EPS);
;                         const float* sp = shw + (size_t)batch_of(r) * INPAD + c0;
;                         v0 = v0 * rstd + *(const f32x4*)sp; v1 = v1 * rstd + *(const f32x4*)(sp + 4);
.LBB0_716:
	s_or_b64 exec, exec, s[24:25]
	v_readlane_b32 s2, v252, 24
	s_add_i32 s15, s8, s2
	v_or_b32_e32 v98, s15, v142
	v_ashrrev_i32_e32 v99, 31, v98
	s_and_b64 vcc, exec, s[38:39]
	v_cmp_gt_i32_e64 s[42:43], s89, v98
	s_cbranch_vccnz .LBB0_718
	v_readlane_b32 s2, v251, 45
	v_readlane_b32 s3, v251, 46
	v_lshlrev_b32_e32 v102, 2, v130
	v_mov_b32_e32 v103, v5
	v_lshl_add_u64 v[100:101], v[98:99], 2, s[2:3]
	s_nop 0
	s_add_i32 s3, s15, 0xffff0000
	s_lshr_b32 s3, s3, 6
	s_ashr_i32 s2, s15, 12
	s_add_i32 s3, s3, 16
	v_mov_b32_e32 v100, s3
	v_mov_b32_e32 v101, s2
	v_cndmask_b32_e64 v100, v100, v101, s[42:43]
	v_ashrrev_i32_e32 v101, 31, v100
	v_lshlrev_b64 v[100:101], 13, v[100:101]
	v_lshl_add_u64 v[100:101], s[56:57], 0, v[100:101]
	v_lshl_add_u64 v[104:105], v[100:101], 0, v[102:103]
	global_load_dwordx4 v[100:103], v[104:105], off
	s_nop 0
	global_load_dwordx4 v[104:107], v[104:105], off offset:16
	s_waitcnt vmcnt(0)
	v_mov_b32_e32 v108, v236
	v_mov_b32_e32 v240, v100
	v_mov_b32_e32 v241, v101
	v_mov_b32_e32 v242, v102
	v_mov_b32_e32 v243, v103
	v_mov_b32_e32 v244, v104
	v_mov_b32_e32 v245, v105
	v_mov_b32_e32 v246, v106
	v_mov_b32_e32 v247, v107
	v_fmamk_f32 v108, v108, 0x3a800000, v214
	v_mul_f32_e32 v109, 0x4b800000, v108
	v_cmp_gt_f32_e32 vcc, s9, v108
	s_nop 1
	v_cndmask_b32_e32 v108, v108, v109, vcc
	v_rsq_f32_e32 v108, v108
	s_nop 0
	v_mul_f32_e32 v109, 0x45800000, v108
	v_cndmask_b32_e32 v108, v108, v109, vcc
	v_pk_fma_f32 v[96:97], v[96:97], v[108:109], v[102:103] op_sel_hi:[1,0,1]
	v_pk_fma_f32 v[94:95], v[94:95], v[108:109], v[100:101] op_sel_hi:[1,0,1]
	v_pk_fma_f32 v[92:93], v[92:93], v[108:109], v[106:107] op_sel_hi:[1,0,1]
	v_pk_fma_f32 v[90:91], v[90:91], v[108:109], v[104:105] op_sel_hi:[1,0,1]

;     __device__ __forceinline__ void operator()(const f32x4 (&acc)[2][2][4][2], const Unit& u, int wr, int wc, int fr, int fq) const {
;     ...
;                     const int r = EPI_ROW(u, ai, wr, m, fr);
;                     f32x4 v0 = acc[ai][bj][m][0], v1 = acc[ai][bj][m][1];
;                     if (rs) {
;                         const float rstd = rsqrtf(rs[r] * (1.f / 1024.f) + EPS);
;                         const float* sp = shw + (size_t)batch_of(r) * INPAD + c0;
;                         v0 = v0 * rstd + *(const f32x4*)sp; v1 = v1 * rstd + *(const f32x4*)(sp + 4);
.LBB0_726:
	s_nop 1
	v_or_b32_e32 v90, s15, v141
	v_ashrrev_i32_e32 v91, 31, v90
	s_and_b64 vcc, exec, s[38:39]
	v_cmp_gt_i32_e64 s[42:43], s89, v90
	s_cbranch_vccnz .LBB0_728
	v_readlane_b32 s2, v251, 45
	v_readlane_b32 s3, v251, 46
	v_lshlrev_b32_e32 v94, 2, v130
	v_mov_b32_e32 v95, v5
	v_lshl_add_u64 v[92:93], v[90:91], 2, s[2:3]
	s_nop 0
	s_add_i32 s3, s15, 0xffff0000
	s_lshr_b32 s3, s3, 6
	s_ashr_i32 s2, s15, 12
	s_add_i32 s3, s3, 16
	v_mov_b32_e32 v92, s3
	v_mov_b32_e32 v93, s2
	v_cndmask_b32_e64 v92, v92, v93, s[42:43]
	v_ashrrev_i32_e32 v93, 31, v92
	v_lshlrev_b64 v[92:93], 13, v[92:93]
	v_lshl_add_u64 v[92:93], s[56:57], 0, v[92:93]
	v_lshl_add_u64 v[96:97], v[92:93], 0, v[94:95]
	s_nop 0
	s_nop 0
	s_nop 0
	v_mov_b32_e32 v100, v237
	v_mov_b32_e32 v92, v240
	v_mov_b32_e32 v93, v241
	v_mov_b32_e32 v94, v242
	v_mov_b32_e32 v95, v243
	v_mov_b32_e32 v96, v244
	v_mov_b32_e32 v97, v245
	v_mov_b32_e32 v98, v246
	v_mov_b32_e32 v99, v247
	v_fmamk_f32 v100, v100, 0x3a800000, v214
	v_mul_f32_e32 v101, 0x4b800000, v100
	v_cmp_gt_f32_e32 vcc, s9, v100
	s_nop 1
	v_cndmask_b32_e32 v100, v100, v101, vcc
	v_rsq_f32_e32 v100, v100
	s_nop 0
	v_mul_f32_e32 v101, 0x45800000, v100
	v_cndmask_b32_e32 v100, v100, v101, vcc
	v_pk_fma_f32 v[88:89], v[88:89], v[100:101], v[94:95] op_sel_hi:[1,0,1]
	v_pk_fma_f32 v[86:87], v[86:87], v[100:101], v[92:93] op_sel_hi:[1,0,1]
	v_pk_fma_f32 v[84:85], v[84:85], v[100:101], v[98:99] op_sel_hi:[1,0,1]
	v_pk_fma_f32 v[82:83], v[82:83], v[100:101], v[96:97] op_sel_hi:[1,0,1]

;     __device__ __forceinline__ void operator()(const f32x4 (&acc)[2][2][4][2], const Unit& u, int wr, int wc, int fr, int fq) const {
;     ...
;                     const int r = EPI_ROW(u, ai, wr, m, fr);
;                     f32x4 v0 = acc[ai][bj][m][0], v1 = acc[ai][bj][m][1];
;                     if (rs) {
;                         const float rstd = rsqrtf(rs[r] * (1.f / 1024.f) + EPS);
;                         const float* sp = shw + (size_t)batch_of(r) * INPAD + c0;
;                         v0 = v0 * rstd + *(const f32x4*)sp; v1 = v1 * rstd + *(const f32x4*)(sp + 4);
.LBB0_736:
	s_nop 1
	v_or_b32_e32 v82, s15, v140
	v_ashrrev_i32_e32 v83, 31, v82
	s_and_b64 vcc, exec, s[38:39]
	v_cmp_gt_i32_e64 s[42:43], s89, v82
	s_cbranch_vccnz .LBB0_738
	v_readlane_b32 s2, v251, 45
	v_readlane_b32 s3, v251, 46
	v_lshlrev_b32_e32 v86, 2, v130
	v_mov_b32_e32 v87, v5
	v_lshl_add_u64 v[84:85], v[82:83], 2, s[2:3]
	s_nop 0
	s_add_i32 s3, s15, 0xffff0000
	s_lshr_b32 s3, s3, 6
	s_ashr_i32 s2, s15, 12
	s_add_i32 s3, s3, 16
	v_mov_b32_e32 v84, s3
	v_mov_b32_e32 v85, s2
	v_cndmask_b32_e64 v84, v84, v85, s[42:43]
	v_ashrrev_i32_e32 v85, 31, v84
	v_lshlrev_b64 v[84:85], 13, v[84:85]
	v_lshl_add_u64 v[84:85], s[56:57], 0, v[84:85]
	v_lshl_add_u64 v[88:89], v[84:85], 0, v[86:87]
	s_nop 0
	s_nop 0
	s_nop 0
	v_mov_b32_e32 v92, v238
	v_mov_b32_e32 v84, v240
	v_mov_b32_e32 v85, v241
	v_mov_b32_e32 v86, v242
	v_mov_b32_e32 v87, v243
	v_mov_b32_e32 v88, v244
	v_mov_b32_e32 v89, v245
	v_mov_b32_e32 v90, v246
	v_mov_b32_e32 v91, v247
	v_fmamk_f32 v92, v92, 0x3a800000, v214
	v_mul_f32_e32 v93, 0x4b800000, v92
	v_cmp_gt_f32_e32 vcc, s9, v92
	s_nop 1
	v_cndmask_b32_e32 v92, v92, v93, vcc
	v_rsq_f32_e32 v92, v92
	s_nop 0
	v_mul_f32_e32 v93, 0x45800000, v92
	v_cndmask_b32_e32 v92, v92, v93, vcc
	v_pk_fma_f32 v[80:81], v[80:81], v[92:93], v[86:87] op_sel_hi:[1,0,1]
	v_pk_fma_f32 v[78:79], v[78:79], v[92:93], v[84:85] op_sel_hi:[1,0,1]
	v_pk_fma_f32 v[76:77], v[76:77], v[92:93], v[90:91] op_sel_hi:[1,0,1]
	v_pk_fma_f32 v[74:75], v[74:75], v[92:93], v[88:89] op_sel_hi:[1,0,1]

;     __device__ __forceinline__ void operator()(const f32x4 (&acc)[2][2][4][2], const Unit& u, int wr, int wc, int fr, int fq) const {
;     ...
;                     const int r = EPI_ROW(u, ai, wr, m, fr);
;                     f32x4 v0 = acc[ai][bj][m][0], v1 = acc[ai][bj][m][1];
;                     if (rs) {
;                         const float rstd = rsqrtf(rs[r] * (1.f / 1024.f) + EPS);
;                         const float* sp = shw + (size_t)batch_of(r) * INPAD + c0;
;                         v0 = v0 * rstd + *(const f32x4*)sp; v1 = v1 * rstd + *(const f32x4*)(sp + 4);
.LBB0_746:
	s_nop 1
	v_or_b32_e32 v74, s15, v131
	v_ashrrev_i32_e32 v75, 31, v74
	s_and_b64 vcc, exec, s[38:39]
	v_cmp_gt_i32_e64 s[42:43], s89, v74
	s_cbranch_vccnz .LBB0_748
	v_readlane_b32 s2, v251, 45
	v_readlane_b32 s3, v251, 46
	v_lshlrev_b32_e32 v78, 2, v130
	v_mov_b32_e32 v79, v5
	v_lshl_add_u64 v[76:77], v[74:75], 2, s[2:3]
	s_nop 0
	s_add_i32 s3, s15, 0xffff0000
	s_lshr_b32 s3, s3, 6
	s_ashr_i32 s2, s15, 12
	s_add_i32 s3, s3, 16
	v_mov_b32_e32 v76, s3
	v_mov_b32_e32 v77, s2
	v_cndmask_b32_e64 v76, v76, v77, s[42:43]
	v_ashrrev_i32_e32 v77, 31, v76
	v_lshlrev_b64 v[76:77], 13, v[76:77]
	v_lshl_add_u64 v[76:77], s[56:57], 0, v[76:77]
	v_lshl_add_u64 v[80:81], v[76:77], 0, v[78:79]
	s_nop 0
	s_nop 0
	s_nop 0
	v_mov_b32_e32 v84, v239
	v_mov_b32_e32 v76, v240
	v_mov_b32_e32 v77, v241
	v_mov_b32_e32 v78, v242
	v_mov_b32_e32 v79, v243
	v_mov_b32_e32 v80, v244
	v_mov_b32_e32 v81, v245
	v_mov_b32_e32 v82, v246
	v_mov_b32_e32 v83, v247
	v_fmamk_f32 v84, v84, 0x3a800000, v214
	v_mul_f32_e32 v85, 0x4b800000, v84
	v_cmp_gt_f32_e32 vcc, s9, v84
	s_nop 1
	v_cndmask_b32_e32 v84, v84, v85, vcc
	v_rsq_f32_e32 v84, v84
	s_nop 0
	v_mul_f32_e32 v85, 0x45800000, v84
	v_cndmask_b32_e32 v84, v84, v85, vcc
	v_pk_fma_f32 v[72:73], v[72:73], v[84:85], v[78:79] op_sel_hi:[1,0,1]
	v_pk_fma_f32 v[70:71], v[70:71], v[84:85], v[76:77] op_sel_hi:[1,0,1]
	v_pk_fma_f32 v[68:69], v[68:69], v[84:85], v[82:83] op_sel_hi:[1,0,1]
	v_pk_fma_f32 v[66:67], v[66:67], v[84:85], v[80:81] op_sel_hi:[1,0,1]

;     __device__ __forceinline__ void operator()(const f32x4 (&acc)[2][2][4][2], const Unit& u, int wr, int wc, int fr, int fq) const {
;     ...
;             const int c0 = u.pn * 256 + bj * 128 + wc * 32 + 8 * fq;
;             if (c0 >= INC) continue;
; #pragma unroll
;             for (int ai = 0; ai < 2; ++ai)
; #pragma unroll
;                 for (int m = 0; m < 4; ++m) {
;                     const int r = EPI_ROW(u, ai, wr, m, fr);
;                     f32x4 v0 = acc[ai][bj][m][0], v1 = acc[ai][bj][m][1];
;                     if (rs) {
;                         const float rstd = rsqrtf(rs[r] * (1.f / 1024.f) + EPS);
;                         const float* sp = shw + (size_t)batch_of(r) * INPAD + c0;
;                         v0 = v0 * rstd + *(const f32x4*)sp; v1 = v1 * rstd + *(const f32x4*)(sp + 4);
.LBB0_766:
	s_or_b64 exec, exec, s[20:21]
	s_nop 0
	v_or_b32_e32 v66, 0x80, v130
	s_movk_i32 s2, 0x720
	v_cmp_gt_u32_e32 vcc, s2, v66
	s_and_saveexec_b64 s[20:21], vcc
	s_cbranch_execz .LBB0_870
	v_readlane_b32 s2, v252, 24
	s_add_i32 s4, s4, s2
	v_or_b32_e32 v74, s4, v142
	v_ashrrev_i32_e32 v75, 31, v74
	s_and_b64 vcc, exec, s[72:73]
	v_cmp_gt_i32_e64 s[40:41], s89, v74
	s_cbranch_vccz .LBB0_769
	v_readlane_b32 s2, v251, 45
	v_readlane_b32 s3, v251, 46
	v_lshlrev_b32_e32 v68, 2, v130
	v_mov_b32_e32 v69, v5
	v_lshl_add_u64 v[66:67], v[74:75], 2, s[2:3]
	s_nop 0
	s_add_i32 s3, s4, 0xffff0000
	s_lshr_b32 s3, s3, 6
	s_ashr_i32 s2, s4, 12
	s_add_i32 s3, s3, 16
	v_mov_b32_e32 v66, s3
	v_mov_b32_e32 v67, s2
	v_cndmask_b32_e64 v66, v66, v67, s[40:41]
	v_ashrrev_i32_e32 v67, 31, v66
	v_lshlrev_b64 v[66:67], 13, v[66:67]
	v_lshl_add_u64 v[66:67], s[56:57], 0, v[66:67]
	v_lshl_add_u64 v[70:71], v[66:67], 0, v[68:69]
	global_load_dwordx4 v[66:69], v[70:71], off offset:512
	s_nop 0
	global_load_dwordx4 v[70:73], v[70:71], off offset:528
	s_waitcnt vmcnt(0)
	v_mov_b32_e32 v76, v232
	v_mov_b32_e32 v240, v66
	v_mov_b32_e32 v241, v67
	v_mov_b32_e32 v242, v68
	v_mov_b32_e32 v243, v69
	v_mov_b32_e32 v244, v70
	v_mov_b32_e32 v245, v71
	v_mov_b32_e32 v246, v72
	v_mov_b32_e32 v247, v73
	v_fmamk_f32 v76, v76, 0x3a800000, v214
	v_mul_f32_e32 v77, 0x4b800000, v76
	v_cmp_gt_f32_e32 vcc, s9, v76
	s_nop 1
	v_cndmask_b32_e32 v76, v76, v77, vcc
	v_rsq_f32_e32 v76, v76
	s_nop 0
	v_mul_f32_e32 v77, 0x45800000, v76
	v_cndmask_b32_e32 v76, v76, v77, vcc
	v_pk_fma_f32 v[68:69], v[64:65], v[76:77], v[68:69] op_sel_hi:[1,0,1]
	v_pk_fma_f32 v[66:67], v[62:63], v[76:77], v[66:67] op_sel_hi:[1,0,1]
	v_pk_fma_f32 v[72:73], v[60:61], v[76:77], v[72:73] op_sel_hi:[1,0,1]
	v_pk_fma_f32 v[70:71], v[58:59], v[76:77], v[70:71] op_sel_hi:[1,0,1]
	s_cbranch_execz .LBB0_770
	s_branch .LBB0_771

;     __device__ __forceinline__ void operator()(const f32x4 (&acc)[2][2][4][2], const Unit& u, int wr, int wc, int fr, int fq) const {
;     ...
;                     const int r = EPI_ROW(u, ai, wr, m, fr);
;                     f32x4 v0 = acc[ai][bj][m][0], v1 = acc[ai][bj][m][1];
;                     if (rs) {
;                         const float rstd = rsqrtf(rs[r] * (1.f / 1024.f) + EPS);
;                         const float* sp = shw + (size_t)batch_of(r) * INPAD + c0;
;                         v0 = v0 * rstd + *(const f32x4*)sp; v1 = v1 * rstd + *(const f32x4*)(sp + 4);
.LBB0_780:
	v_or_b32_e32 v62, s4, v141
	v_ashrrev_i32_e32 v63, 31, v62
	s_and_b64 vcc, exec, s[38:39]
	v_cmp_gt_i32_e64 s[42:43], s89, v62
	s_cbranch_vccnz .LBB0_782
	v_readlane_b32 s2, v251, 45
	v_readlane_b32 s3, v251, 46
	s_nop 1
	v_lshl_add_u64 v[64:65], v[62:63], 2, s[2:3]
	s_nop 0
	s_add_i32 s3, s4, 0xffff0000
	s_lshr_b32 s3, s3, 6
	s_ashr_i32 s2, s4, 12
	s_add_i32 s3, s3, 16
	v_mov_b32_e32 v59, s3
	v_mov_b32_e32 v64, s2
	v_cndmask_b32_e64 v64, v59, v64, s[42:43]
	v_ashrrev_i32_e32 v65, 31, v64
	v_lshlrev_b64 v[64:65], 13, v[64:65]
	v_lshl_add_u64 v[64:65], s[56:57], 0, v[64:65]
	v_mov_b32_e32 v59, v5
	v_lshl_add_u64 v[68:69], v[64:65], 0, v[58:59]
	s_nop 0
	s_nop 0
	s_nop 0
	v_mov_b32_e32 v61, v233
	v_mov_b32_e32 v64, v240
	v_mov_b32_e32 v65, v241
	v_mov_b32_e32 v66, v242
	v_mov_b32_e32 v67, v243
	v_mov_b32_e32 v68, v244
	v_mov_b32_e32 v69, v245
	v_mov_b32_e32 v70, v246
	v_mov_b32_e32 v71, v247
	v_fmamk_f32 v59, v61, 0x3a800000, v214
	v_mul_f32_e32 v61, 0x4b800000, v59
	v_cmp_gt_f32_e32 vcc, s9, v59
	s_nop 1
	v_cndmask_b32_e32 v59, v59, v61, vcc
	v_rsq_f32_e32 v59, v59
	s_nop 0
	v_mul_f32_e32 v61, 0x45800000, v59
	v_cndmask_b32_e32 v72, v59, v61, vcc
	v_pk_fma_f32 v[56:57], v[56:57], v[72:73], v[66:67] op_sel_hi:[1,0,1]
	v_pk_fma_f32 v[54:55], v[54:55], v[72:73], v[64:65] op_sel_hi:[1,0,1]
	v_pk_fma_f32 v[52:53], v[52:53], v[72:73], v[70:71] op_sel_hi:[1,0,1]
	v_pk_fma_f32 v[50:51], v[50:51], v[72:73], v[68:69] op_sel_hi:[1,0,1]

;     __device__ __forceinline__ void operator()(const f32x4 (&acc)[2][2][4][2], const Unit& u, int wr, int wc, int fr, int fq) const {
;     ...
;                     const int r = EPI_ROW(u, ai, wr, m, fr);
;                     f32x4 v0 = acc[ai][bj][m][0], v1 = acc[ai][bj][m][1];
;                     if (rs) {
;                         const float rstd = rsqrtf(rs[r] * (1.f / 1024.f) + EPS);
;                         const float* sp = shw + (size_t)batch_of(r) * INPAD + c0;
;                         v0 = v0 * rstd + *(const f32x4*)sp; v1 = v1 * rstd + *(const f32x4*)(sp + 4);
.LBB0_790:
	s_nop 1
	v_or_b32_e32 v50, s4, v140
	v_ashrrev_i32_e32 v51, 31, v50
	s_and_b64 vcc, exec, s[38:39]
	v_cmp_gt_i32_e64 s[42:43], s89, v50
	s_cbranch_vccnz .LBB0_792
	v_readlane_b32 s2, v251, 45
	v_readlane_b32 s3, v251, 46
	v_mov_b32_e32 v59, v5
	s_nop 0
	v_lshl_add_u64 v[52:53], v[50:51], 2, s[2:3]
	s_nop 0
	s_add_i32 s3, s4, 0xffff0000
	s_lshr_b32 s3, s3, 6
	s_ashr_i32 s2, s4, 12
	s_add_i32 s3, s3, 16
	v_mov_b32_e32 v52, s3
	v_mov_b32_e32 v53, s2
	v_cndmask_b32_e64 v52, v52, v53, s[42:43]
	v_ashrrev_i32_e32 v53, 31, v52
	v_lshlrev_b64 v[52:53], 13, v[52:53]
	v_lshl_add_u64 v[52:53], s[56:57], 0, v[52:53]
	v_lshl_add_u64 v[56:57], v[52:53], 0, v[58:59]
	s_nop 0
	s_nop 0
	v_mov_b32_e32 v61, v234
	v_mov_b32_e32 v52, v240
	v_mov_b32_e32 v53, v241
	v_mov_b32_e32 v54, v242
	v_mov_b32_e32 v55, v243
	v_mov_b32_e32 v62, v244
	v_mov_b32_e32 v63, v245
	v_mov_b32_e32 v64, v246
	v_mov_b32_e32 v65, v247
	v_fmamk_f32 v56, v61, 0x3a800000, v214
	v_mul_f32_e32 v57, 0x4b800000, v56
	v_cmp_gt_f32_e32 vcc, s9, v56
	s_nop 1
	v_cndmask_b32_e32 v56, v56, v57, vcc
	v_rsq_f32_e32 v56, v56
	s_nop 0
	v_mul_f32_e32 v57, 0x45800000, v56
	v_cndmask_b32_e32 v56, v56, v57, vcc
	v_pk_fma_f32 v[48:49], v[48:49], v[56:57], v[54:55] op_sel_hi:[1,0,1]
	v_pk_fma_f32 v[46:47], v[46:47], v[56:57], v[52:53] op_sel_hi:[1,0,1]
	v_pk_fma_f32 v[44:45], v[44:45], v[56:57], v[64:65] op_sel_hi:[1,0,1]
	v_pk_fma_f32 v[42:43], v[42:43], v[56:57], v[62:63] op_sel_hi:[1,0,1]

;     __device__ __forceinline__ void operator()(const f32x4 (&acc)[2][2][4][2], const Unit& u, int wr, int wc, int fr, int fq) const {
;     ...
;                     const int r = EPI_ROW(u, ai, wr, m, fr);
;                     f32x4 v0 = acc[ai][bj][m][0], v1 = acc[ai][bj][m][1];
;                     if (rs) {
;                         const float rstd = rsqrtf(rs[r] * (1.f / 1024.f) + EPS);
;                         const float* sp = shw + (size_t)batch_of(r) * INPAD + c0;
;                         v0 = v0 * rstd + *(const f32x4*)sp; v1 = v1 * rstd + *(const f32x4*)(sp + 4);
.LBB0_800:
	s_nop 1
	v_or_b32_e32 v42, s4, v131
	v_ashrrev_i32_e32 v43, 31, v42
	s_and_b64 vcc, exec, s[38:39]
	v_cmp_gt_i32_e64 s[42:43], s89, v42
	s_cbranch_vccnz .LBB0_802
	v_readlane_b32 s2, v251, 45
	v_readlane_b32 s3, v251, 46
	v_mov_b32_e32 v59, v5
	s_nop 0
	v_lshl_add_u64 v[44:45], v[42:43], 2, s[2:3]
	s_nop 0
	s_add_i32 s3, s4, 0xffff0000
	s_lshr_b32 s3, s3, 6
	s_ashr_i32 s2, s4, 12
	s_add_i32 s3, s3, 16
	v_mov_b32_e32 v44, s3
	v_mov_b32_e32 v45, s2
	v_cndmask_b32_e64 v44, v44, v45, s[42:43]
	v_ashrrev_i32_e32 v45, 31, v44
	v_lshlrev_b64 v[44:45], 13, v[44:45]
	v_lshl_add_u64 v[44:45], s[56:57], 0, v[44:45]
	v_lshl_add_u64 v[48:49], v[44:45], 0, v[58:59]
	s_nop 0
	s_nop 0
	s_nop 0
	v_mov_b32_e32 v52, v235
	v_mov_b32_e32 v44, v240
	v_mov_b32_e32 v45, v241
	v_mov_b32_e32 v46, v242
	v_mov_b32_e32 v47, v243
	v_mov_b32_e32 v48, v244
	v_mov_b32_e32 v49, v245
	v_mov_b32_e32 v50, v246
	v_mov_b32_e32 v51, v247
	v_fmamk_f32 v52, v52, 0x3a800000, v214
	v_mul_f32_e32 v53, 0x4b800000, v52
	v_cmp_gt_f32_e32 vcc, s9, v52
	s_nop 1
	v_cndmask_b32_e32 v52, v52, v53, vcc
	v_rsq_f32_e32 v52, v52
	s_nop 0
	v_mul_f32_e32 v53, 0x45800000, v52
	v_cndmask_b32_e32 v52, v52, v53, vcc
	v_pk_fma_f32 v[40:41], v[40:41], v[52:53], v[46:47] op_sel_hi:[1,0,1]
	v_pk_fma_f32 v[38:39], v[38:39], v[52:53], v[44:45] op_sel_hi:[1,0,1]
	v_pk_fma_f32 v[36:37], v[36:37], v[52:53], v[50:51] op_sel_hi:[1,0,1]
	v_pk_fma_f32 v[34:35], v[34:35], v[52:53], v[48:49] op_sel_hi:[1,0,1]

;     __device__ __forceinline__ void operator()(const f32x4 (&acc)[2][2][4][2], const Unit& u, int wr, int wc, int fr, int fq) const {
;     ...
;                     const int r = EPI_ROW(u, ai, wr, m, fr);
;                     f32x4 v0 = acc[ai][bj][m][0], v1 = acc[ai][bj][m][1];
;                     if (rs) {
;                         const float rstd = rsqrtf(rs[r] * (1.f / 1024.f) + EPS);
;                         const float* sp = shw + (size_t)batch_of(r) * INPAD + c0;
;                         v0 = v0 * rstd + *(const f32x4*)sp; v1 = v1 * rstd + *(const f32x4*)(sp + 4);
.LBB0_820:
	s_or_b64 exec, exec, s[24:25]
	v_readlane_b32 s2, v252, 24
	s_add_i32 s4, s8, s2
	v_or_b32_e32 v34, s4, v142
	v_ashrrev_i32_e32 v35, 31, v34
	s_and_b64 vcc, exec, s[38:39]
	v_cmp_gt_i32_e64 s[42:43], s89, v34
	s_cbranch_vccnz .LBB0_822
	v_readlane_b32 s2, v251, 45
	v_readlane_b32 s3, v251, 46
	v_mov_b32_e32 v59, v5
	s_nop 0
	v_lshl_add_u64 v[36:37], v[34:35], 2, s[2:3]
	s_nop 0
	s_add_i32 s3, s4, 0xffff0000
	s_lshr_b32 s3, s3, 6
	s_ashr_i32 s2, s4, 12
	s_add_i32 s3, s3, 16
	v_mov_b32_e32 v36, s3
	v_mov_b32_e32 v37, s2
	v_cndmask_b32_e64 v36, v36, v37, s[42:43]
	v_ashrrev_i32_e32 v37, 31, v36
	v_lshlrev_b64 v[36:37], 13, v[36:37]
	v_lshl_add_u64 v[36:37], s[56:57], 0, v[36:37]
	v_lshl_add_u64 v[40:41], v[36:37], 0, v[58:59]
	global_load_dwordx4 v[36:39], v[40:41], off offset:512
	s_nop 0
	global_load_dwordx4 v[40:43], v[40:41], off offset:528
	s_waitcnt vmcnt(0)
	v_mov_b32_e32 v44, v236
	v_mov_b32_e32 v240, v36
	v_mov_b32_e32 v241, v37
	v_mov_b32_e32 v242, v38
	v_mov_b32_e32 v243, v39
	v_mov_b32_e32 v244, v40
	v_mov_b32_e32 v245, v41
	v_mov_b32_e32 v246, v42
	v_mov_b32_e32 v247, v43
	v_fmamk_f32 v44, v44, 0x3a800000, v214
	v_mul_f32_e32 v45, 0x4b800000, v44
	v_cmp_gt_f32_e32 vcc, s9, v44
	s_nop 1
	v_cndmask_b32_e32 v44, v44, v45, vcc
	v_rsq_f32_e32 v44, v44
	s_nop 0
	v_mul_f32_e32 v45, 0x45800000, v44
	v_cndmask_b32_e32 v44, v44, v45, vcc
	v_pk_fma_f32 v[32:33], v[32:33], v[44:45], v[38:39] op_sel_hi:[1,0,1]
	v_pk_fma_f32 v[30:31], v[30:31], v[44:45], v[36:37] op_sel_hi:[1,0,1]
	v_pk_fma_f32 v[28:29], v[28:29], v[44:45], v[42:43] op_sel_hi:[1,0,1]
	v_pk_fma_f32 v[26:27], v[26:27], v[44:45], v[40:41] op_sel_hi:[1,0,1]

;     __device__ __forceinline__ void operator()(const f32x4 (&acc)[2][2][4][2], const Unit& u, int wr, int wc, int fr, int fq) const {
;     ...
;                     const int r = EPI_ROW(u, ai, wr, m, fr);
;                     f32x4 v0 = acc[ai][bj][m][0], v1 = acc[ai][bj][m][1];
;                     if (rs) {
;                         const float rstd = rsqrtf(rs[r] * (1.f / 1024.f) + EPS);
;                         const float* sp = shw + (size_t)batch_of(r) * INPAD + c0;
;                         v0 = v0 * rstd + *(const f32x4*)sp; v1 = v1 * rstd + *(const f32x4*)(sp + 4);
.LBB0_830:
	s_nop 1
	v_or_b32_e32 v26, s4, v141
	v_ashrrev_i32_e32 v27, 31, v26
	s_and_b64 vcc, exec, s[38:39]
	v_cmp_gt_i32_e64 s[42:43], s89, v26
	s_cbranch_vccnz .LBB0_832
	v_readlane_b32 s2, v251, 45
	v_readlane_b32 s3, v251, 46
	v_mov_b32_e32 v59, v5
	s_nop 0
	v_lshl_add_u64 v[28:29], v[26:27], 2, s[2:3]
	s_nop 0
	s_add_i32 s3, s4, 0xffff0000
	s_lshr_b32 s3, s3, 6
	s_ashr_i32 s2, s4, 12
	s_add_i32 s3, s3, 16
	v_mov_b32_e32 v28, s3
	v_mov_b32_e32 v29, s2
	v_cndmask_b32_e64 v28, v28, v29, s[42:43]
	v_ashrrev_i32_e32 v29, 31, v28
	v_lshlrev_b64 v[28:29], 13, v[28:29]
	v_lshl_add_u64 v[28:29], s[56:57], 0, v[28:29]
	v_lshl_add_u64 v[32:33], v[28:29], 0, v[58:59]
	s_nop 0
	s_nop 0
	s_nop 0
	v_mov_b32_e32 v36, v237
	v_mov_b32_e32 v28, v240
	v_mov_b32_e32 v29, v241
	v_mov_b32_e32 v30, v242
	v_mov_b32_e32 v31, v243
	v_mov_b32_e32 v32, v244
	v_mov_b32_e32 v33, v245
	v_mov_b32_e32 v34, v246
	v_mov_b32_e32 v35, v247
	v_fmamk_f32 v36, v36, 0x3a800000, v214
	v_mul_f32_e32 v37, 0x4b800000, v36
	v_cmp_gt_f32_e32 vcc, s9, v36
	s_nop 1
	v_cndmask_b32_e32 v36, v36, v37, vcc
	v_rsq_f32_e32 v36, v36
	s_nop 0
	v_mul_f32_e32 v37, 0x45800000, v36
	v_cndmask_b32_e32 v36, v36, v37, vcc
	v_pk_fma_f32 v[24:25], v[24:25], v[36:37], v[30:31] op_sel_hi:[1,0,1]
	v_pk_fma_f32 v[22:23], v[22:23], v[36:37], v[28:29] op_sel_hi:[1,0,1]
	v_pk_fma_f32 v[20:21], v[20:21], v[36:37], v[34:35] op_sel_hi:[1,0,1]
	v_pk_fma_f32 v[18:19], v[18:19], v[36:37], v[32:33] op_sel_hi:[1,0,1]

;     __device__ __forceinline__ void operator()(const f32x4 (&acc)[2][2][4][2], const Unit& u, int wr, int wc, int fr, int fq) const {
;     ...
;                     const int r = EPI_ROW(u, ai, wr, m, fr);
;                     f32x4 v0 = acc[ai][bj][m][0], v1 = acc[ai][bj][m][1];
;                     if (rs) {
;                         const float rstd = rsqrtf(rs[r] * (1.f / 1024.f) + EPS);
;                         const float* sp = shw + (size_t)batch_of(r) * INPAD + c0;
;                         v0 = v0 * rstd + *(const f32x4*)sp; v1 = v1 * rstd + *(const f32x4*)(sp + 4);
.LBB0_840:
	s_nop 1
	v_or_b32_e32 v18, s4, v140
	v_ashrrev_i32_e32 v19, 31, v18
	s_and_b64 vcc, exec, s[38:39]
	v_cmp_gt_i32_e64 s[42:43], s89, v18
	s_cbranch_vccnz .LBB0_842
	v_readlane_b32 s2, v251, 45
	v_readlane_b32 s3, v251, 46
	v_mov_b32_e32 v59, v5
	s_nop 0
	v_lshl_add_u64 v[20:21], v[18:19], 2, s[2:3]
	s_nop 0
	s_add_i32 s3, s4, 0xffff0000
	s_lshr_b32 s3, s3, 6
	s_ashr_i32 s2, s4, 12
	s_add_i32 s3, s3, 16
	v_mov_b32_e32 v20, s3
	v_mov_b32_e32 v21, s2
	v_cndmask_b32_e64 v20, v20, v21, s[42:43]
	v_ashrrev_i32_e32 v21, 31, v20
	v_lshlrev_b64 v[20:21], 13, v[20:21]
	v_lshl_add_u64 v[20:21], s[56:57], 0, v[20:21]
	v_lshl_add_u64 v[24:25], v[20:21], 0, v[58:59]
	s_nop 0
	s_nop 0
	s_nop 0
	v_mov_b32_e32 v28, v238
	v_mov_b32_e32 v20, v240
	v_mov_b32_e32 v21, v241
	v_mov_b32_e32 v22, v242
	v_mov_b32_e32 v23, v243
	v_mov_b32_e32 v24, v244
	v_mov_b32_e32 v25, v245
	v_mov_b32_e32 v26, v246
	v_mov_b32_e32 v27, v247
	v_fmamk_f32 v28, v28, 0x3a800000, v214
	v_mul_f32_e32 v29, 0x4b800000, v28
	v_cmp_gt_f32_e32 vcc, s9, v28
	s_nop 1
	v_cndmask_b32_e32 v28, v28, v29, vcc
	v_rsq_f32_e32 v28, v28
	s_nop 0
	v_mul_f32_e32 v29, 0x45800000, v28
	v_cndmask_b32_e32 v28, v28, v29, vcc
	v_pk_fma_f32 v[16:17], v[16:17], v[28:29], v[22:23] op_sel_hi:[1,0,1]
	v_pk_fma_f32 v[14:15], v[14:15], v[28:29], v[20:21] op_sel_hi:[1,0,1]
	v_pk_fma_f32 v[12:13], v[12:13], v[28:29], v[26:27] op_sel_hi:[1,0,1]
	v_pk_fma_f32 v[10:11], v[10:11], v[28:29], v[24:25] op_sel_hi:[1,0,1]

;     __device__ __forceinline__ void operator()(const f32x4 (&acc)[2][2][4][2], const Unit& u, int wr, int wc, int fr, int fq) const {
;     ...
;                     const int r = EPI_ROW(u, ai, wr, m, fr);
;                     f32x4 v0 = acc[ai][bj][m][0], v1 = acc[ai][bj][m][1];
;                     if (rs) {
;                         const float rstd = rsqrtf(rs[r] * (1.f / 1024.f) + EPS);
;                         const float* sp = shw + (size_t)batch_of(r) * INPAD + c0;
;                         v0 = v0 * rstd + *(const f32x4*)sp; v1 = v1 * rstd + *(const f32x4*)(sp + 4);
.LBB0_850:
	s_nop 1
	v_or_b32_e32 v10, s4, v131
	v_ashrrev_i32_e32 v11, 31, v10
	s_and_b64 vcc, exec, s[38:39]
	v_cmp_gt_i32_e64 s[38:39], s89, v10
	s_cbranch_vccnz .LBB0_852
	v_readlane_b32 s2, v251, 45
	v_readlane_b32 s3, v251, 46
	v_mov_b32_e32 v59, v5
	s_nop 0
	v_lshl_add_u64 v[12:13], v[10:11], 2, s[2:3]
	s_nop 0
	s_add_i32 s3, s4, 0xffff0000
	s_lshr_b32 s3, s3, 6
	s_ashr_i32 s2, s4, 12
	s_add_i32 s3, s3, 16
	v_mov_b32_e32 v12, s3
	v_mov_b32_e32 v13, s2
	v_cndmask_b32_e64 v12, v12, v13, s[38:39]
	v_ashrrev_i32_e32 v13, 31, v12
	v_lshlrev_b64 v[12:13], 13, v[12:13]
	v_lshl_add_u64 v[12:13], s[56:57], 0, v[12:13]
	v_lshl_add_u64 v[16:17], v[12:13], 0, v[58:59]
	s_nop 0
	s_nop 0
	s_nop 0
	v_mov_b32_e32 v20, v239
	v_mov_b32_e32 v12, v240
	v_mov_b32_e32 v13, v241
	v_mov_b32_e32 v14, v242
	v_mov_b32_e32 v15, v243
	v_mov_b32_e32 v16, v244
	v_mov_b32_e32 v17, v245
	v_mov_b32_e32 v18, v246
	v_mov_b32_e32 v19, v247
	v_fmamk_f32 v20, v20, 0x3a800000, v214
	v_mul_f32_e32 v21, 0x4b800000, v20
	v_cmp_gt_f32_e32 vcc, s9, v20
	s_nop 1
	v_cndmask_b32_e32 v20, v20, v21, vcc
	v_rsq_f32_e32 v20, v20
	s_nop 0
	v_mul_f32_e32 v21, 0x45800000, v20
	v_cndmask_b32_e32 v20, v20, v21, vcc
	v_pk_fma_f32 v[8:9], v[8:9], v[20:21], v[14:15] op_sel_hi:[1,0,1]
	v_pk_fma_f32 v[6:7], v[6:7], v[20:21], v[12:13] op_sel_hi:[1,0,1]
	v_pk_fma_f32 v[2:3], v[2:3], v[20:21], v[18:19] op_sel_hi:[1,0,1]
	v_pk_fma_f32 v[0:1], v[0:1], v[20:21], v[16:17] op_sel_hi:[1,0,1]
